# K/V projection GEMM moved from the head of P2 to the tail of P3 (workgroups 49..255, 49..97 take two tiles)
# speedup vs baseline: 1.0025x; 1.0025x over previous
; __global__ void __launch_bounds__(512, 2) hybrid_fwd(Args unused_args) {
;     ...
; for (int rep_ = 0; rep_ < REP_QKV; ++rep_) {
;     ...
;         { PH_LOCALS
;           pg8::Gemm g{Hh + C_CKV, (const bf16_t*)(wb + W_UKV), T, 512, 256, HP}; pg8::StaticOrder S; S.init(T, 512, G, bid);
;           EpiKV E{(bf16_t*)((unsigned char*)a.out + DO_K), (bf16_t*)((unsigned char*)a.out + DO_V), Hh, (const float*)(ws + WS_SSQKV), (const float*)(ws + WS_ROPE16)};
;           pg8::gemm_phase<EpiKV, pg8::StaticOrder, true, true>(lds, g, S, E, wv0); }
;     ...
; }
; for (int rep_ = 0; rep_ < REP_MIX1; ++rep_) {
;     ...
;         { PH_LOCALS const LayerP P = layer_params(ka, l);
;           for (int r2_ = 0; r2_ < REP_SSD; ++r2_)
;           for (int u = bid; u < NB * NCH; u += G) ssd_pass1(lds, a, P, u, wv0); }
.LBB0_867:
	s_or_b64 exec, exec, s[16:17]
	v_readlane_b32 s2, v254, 50
	v_readlane_b32 s3, v254, 51
	s_xor_b64 s[2:3], s[2:3], -1
	v_writelane_b32 v254, s2, 56
	s_waitcnt lgkmcnt(0)
	s_barrier
	v_writelane_b32 v254, s3, 57
	s_nop 0
.LBB0_927:
	v_readlane_b32 s2, v254, 48
	s_lshl_b32 s44, s2, 2
	s_mul_i32 s58, s2, 0xc00
	s_mulk_i32 s2, 0x300
	s_mov_b32 s3, s59
	v_writelane_b32 v255, s2, 3
	s_mov_b32 s7, s77
	s_mov_b32 s34, s87
	v_writelane_b32 v255, s3, 4
	v_readlane_b32 s2, v254, 2
	v_readlane_b32 s3, v254, 3
	v_readlane_b32 s12, v254, 0
	s_mov_b32 s45, s59
	v_mbcnt_lo_u32_b32 v0, -1, 0
	v_mbcnt_hi_u32_b32 v0, -1, v0
	s_mov_b32 s35, s12
	s_cmpk_gt_i32 s34, 0xff
	v_readlane_b32 s13, v254, 1
	s_cbranch_scc1 .LBB0_996
	s_load_dwordx8 s[12:19], s[2:3], 0x38
	s_load_dwordx4 s[36:39], s[2:3], 0xf0
	s_lshl_b64 s[2:3], s[58:59], 2
	s_waitcnt lgkmcnt(0)
	s_add_u32 s42, s12, s2
	s_addc_u32 s43, s13, s3
	v_readlane_b32 s2, v255, 3
	v_readlane_b32 s3, v255, 4
	s_lshl_b64 s[2:3], s[2:3], 2
	s_add_u32 s46, s14, s2
	s_addc_u32 s47, s15, s3
	s_lshl_b64 s[2:3], s[44:45], 2
	s_add_u32 s7, s16, s2
	s_addc_u32 s12, s17, s3
	s_add_u32 s2, s18, s2
	s_addc_u32 s3, s19, s3
	v_readlane_b32 s13, v254, 43
	s_add_u32 s48, s7, s13
	s_addc_u32 s49, s12, 0
	s_add_u32 s50, s2, s13
	s_addc_u32 s51, s3, 0
	s_add_u32 s2, s38, s13
	s_addc_u32 s3, s39, 0
	s_add_u32 s94, s2, 0x2500000
	s_addc_u32 s95, s3, 0
	v_readlane_b32 s2, v254, 44
	s_add_u32 s2, s36, s2
	s_addc_u32 s3, s37, 0
	s_add_u32 s40, s2, 0x3000000
	s_addc_u32 s41, s3, 0
	s_add_u32 s36, s38, 0x2680000
	s_addc_u32 s37, s39, 0
	s_branch .LBB0_930

;   __device__ __forceinline__ bool next(int i,AttnUnit&u)const{ const int pair=vcu+(i>>1)*G; if(pair>=BATCH*NHEAD*(NQB/2))return false; const int s=pair%(NQB/2); u.bh=pair/(NQB/2); u.qb=(i&1)?(NQB-1-s):s; return true; }
;     __host__ __device__ bool next(int i, Unit& u) const {
;         const long L = (long)i * G + c; if (L >= nwg) return false;
;         int wgid = (int)L; { const int q = nwg / NXCD, r = nwg % NXCD, xcd = wgid % NXCD, off = wgid / NXCD; wgid = (xcd < r ? xcd * (q + 1) : r * (q + 1) + (xcd - r) * q) + off; }
;         const int nig = WGM * nN, gid = wgid / nig, fm = gid * WGM, gsz = (nM - fm) < WGM ? (nM - fm) : WGM;
;         u.pm = fm + ((wgid % nig) % gsz); u.pn = (wgid % nig) / gsz; return true;
; __global__ void __launch_bounds__(512, 2) hybrid_fwd(Args unused_args) {
;     ...
; for (int rep_ = 0; rep_ < REP_QKV; ++rep_) {
;     ...
;         { PH_LOCALS
;           pg8::Gemm g{Hh + C_CKV, (const bf16_t*)(wb + W_UKV), T, 512, 256, HP}; pg8::StaticOrder S; S.init(T, 512, G, bid);
;           EpiKV E{(bf16_t*)((unsigned char*)a.out + DO_K), (bf16_t*)((unsigned char*)a.out + DO_V), Hh, (const float*)(ws + WS_SSQKV), (const float*)(ws + WS_ROPE16)};
;           pg8::gemm_phase<EpiKV, pg8::StaticOrder, true, true>(lds, g, S, E, wv0); }
;     ...
; }
.LBB0_1310:
	s_waitcnt lgkmcnt(0)
	s_cmpk_lt_u32 s87, 0x31
	s_cbranch_scc1 .Lmy_kv_skip
	v_writelane_b32 v255, s44, 40
	v_writelane_b32 v255, s45, 41
	v_writelane_b32 v255, s58, 42
	v_readlane_b32 s2, v254, 63
	v_readlane_b32 s3, v255, 1
	s_nop 1
	v_writelane_b32 v255, s2, 43
	v_writelane_b32 v255, s3, 44
	s_nop 1
	v_readlane_b32 s2, v255, 3
	v_readlane_b32 s3, v255, 4
	s_nop 1
	v_writelane_b32 v255, s2, 45
	v_writelane_b32 v255, s3, 46
	s_mov_b32 s2, 0
	s_nop 1
	v_writelane_b32 v255, s2, 47
.Lmy_kv_pass:
	s_movk_i32 s82, 0x210
	s_mov_b32 s83, 0xc2fc0000
	s_mov_b64 s[90:91], 0x100000
	s_mov_b64 s[52:53], 0x8000
	s_nop 1
	v_readlane_b32 s2, v255, 47
	s_nop 1
	s_mul_i32 s2, s2, 0xcf
	s_add_i32 s7, s87, s2
	s_sub_i32 s7, s7, 49
	v_readlane_b32 s2, v254, 2
	v_readlane_b32 s3, v254, 3
	s_load_dwordx4 s[20:23], s[2:3], 0xf0
	s_mov_b32 s2, s77
	v_mbcnt_lo_u32_b32 v0, -1, 0
	v_mbcnt_hi_u32_b32 v0, -1, v0
	s_nop 0
	v_readlane_b32 s2, v254, 0
	s_mov_b32 s12, s2
	s_mov_b32 s2, s77
	v_readlane_b32 s3, v254, 1
	v_mbcnt_lo_u32_b32 v10, -1, 0
	v_mbcnt_hi_u32_b32 v10, -1, v10
	s_cmpk_lt_i32 s7, 0x100
	v_lshl_or_b32 v0, s2, 6, v10
	s_cselect_b64 s[2:3], -1, 0
	v_readfirstlane_b32 s14, v0
	v_writelane_b32 v254, s7, 58
	s_and_b64 vcc, exec, s[2:3]
	s_cbranch_vccz .LBB0_873
	v_readlane_b32 s15, v254, 58
	s_ashr_i32 s7, s15, 31
	s_lshr_b32 s7, s7, 29
	s_add_i32 s7, s15, s7
	s_and_b32 s13, s7, -8
	s_sub_i32 s13, s15, s13
	s_cmp_gt_i32 s13, -1
	s_mov_b64 s[16:17], -1
	s_cbranch_scc0 .LBB0_870
	s_lshl_b32 s15, s13, 5
	s_mov_b64 s[16:17], 0

; __global__ void __launch_bounds__(512, 2) hybrid_fwd(Args unused_args) {
;     ...
; for (int rep_ = 0; rep_ < REP_QKV; ++rep_) {
;     ...
;         { PH_LOCALS
;           pg8::Gemm g{Hh + C_CKV, (const bf16_t*)(wb + W_UKV), T, 512, 256, HP}; pg8::StaticOrder S; S.init(T, 512, G, bid);
;           EpiKV E{(bf16_t*)((unsigned char*)a.out + DO_K), (bf16_t*)((unsigned char*)a.out + DO_V), Hh, (const float*)(ws + WS_SSQKV), (const float*)(ws + WS_ROPE16)};
;           pg8::gemm_phase<EpiKV, pg8::StaticOrder, true, true>(lds, g, S, E, wv0); }
;     ...
; }
.Lmy_kv_done:
	v_readlane_b32 s2, v255, 47
	s_nop 1
	s_add_i32 s2, s2, 1
	s_nop 1
	v_writelane_b32 v255, s2, 47
	s_cmp_eq_u32 s2, 1
	s_cbranch_scc0 .Lmy_kv_end
	s_cmpk_lt_u32 s87, 0x62
	s_cbranch_scc1 .Lmy_kv_pass
.Lmy_kv_end:
	v_readlane_b32 s44, v255, 40
	v_readlane_b32 s45, v255, 41
	v_readlane_b32 s58, v255, 42
	v_readlane_b32 s2, v255, 43
	v_readlane_b32 s3, v255, 44
	s_nop 1
	v_writelane_b32 v254, s2, 63
	v_writelane_b32 v255, s3, 1
	s_nop 1
	v_readlane_b32 s2, v255, 45
	v_readlane_b32 s3, v255, 46
	s_nop 1
	v_writelane_b32 v255, s2, 3
	v_writelane_b32 v255, s3, 4
	s_nop 1
